# cvt offload, no extra sleep after the 8 conversion tiles (layer-0 in-projection skew = conversion time only)
# baseline (speedup 1.0000x reference)
.LBB0_241:
	s_or_b64 exec, exec, s[0:1]
	v_readlane_b32 s2, v253, 26
	v_readlane_b32 s3, v253, 27
	s_mov_b64 s[0:1], 0
	s_andn2_b64 vcc, exec, s[2:3]
	s_waitcnt lgkmcnt(0)
	s_barrier
	s_cbranch_vccnz .LBB0_243
	v_readlane_b32 s2, v252, 23
	s_nop 3
	s_cmp_eq_u32 s2, 0
	s_cbranch_scc1 .Lcw_sleep
	v_readlane_b32 s28, v253, 4
	v_readlane_b32 s29, v253, 5
	v_readlane_b32 s30, v253, 6
	v_readlane_b32 s31, v253, 7
	v_lshrrev_b32_e32 v120, 4, v197
	v_and_b32_e32 v121, 15, v197
	v_lshlrev_b32_e32 v121, 2, v121
	v_lshl_add_u32 v122, v120, 10, v121
	v_lshlrev_b32_e32 v122, 2, v122
	v_mul_u32_u24_e32 v123, 0x41, v120
	v_add_u32_e32 v123, v123, v121
	v_lshlrev_b32_e32 v123, 2, v123
	v_lshrrev_b32_e32 v124, 3, v197
	v_and_b32_e32 v125, 7, v197
	v_lshlrev_b32_e32 v125, 3, v125
	v_bfe_u32 v127, v124, 2, 2
	v_lshlrev_b32_e32 v127, 3, v127
	v_bfe_u32 v136, v124, 4, 1
	v_lshl_add_u32 v127, v136, 2, v127
	v_and_b32_e32 v136, 3, v124
	v_add_u32_e32 v127, v127, v136
	v_and_b32_e32 v136, 32, v124
	v_add_u32_e32 v127, v127, v136
	v_mul_u32_u24_e32 v136, 0x41, v125
	v_add_u32_e32 v136, v136, v127
	v_lshlrev_b32_e32 v136, 2, v136
	v_lshl_add_u32 v137, v124, 10, v125
	v_lshlrev_b32_e32 v137, 1, v137
	s_sub_i32 s2, s52, 0x80
	s_add_i32 s4, s2, 0
	s_cmpk_lt_u32 s4, 0x200
	s_cselect_b32 s6, s28, s30
	s_cselect_b32 s7, s29, s31
	s_mov_b32 s16, 0x10500000
	s_cselect_b32 s16, 0x10100000, s16
	s_bfe_u32 s5, s4, 0x10008
	s_lshl_b32 s3, s5, 22
	s_add_u32 s6, s6, s3
	s_addc_u32 s7, s7, 0
	s_lshl_b32 s3, s5, 21
	s_add_i32 s16, s16, s3
	s_and_b32 s3, s4, 15
	s_bfe_u32 s5, s4, 0x40004
	s_lshl_b32 s17, s3, 18
	s_lshl_b32 s20, s5, 8
	s_add_i32 s17, s17, s20
	s_add_u32 s6, s6, s17
	s_addc_u32 s7, s7, 0
	s_add_u32 s12, s6, 0x20000
	s_addc_u32 s13, s7, 0
	s_lshl_b32 s17, s5, 17
	s_lshl_b32 s20, s3, 7
	s_add_i32 s17, s17, s20
	s_add_i32 s16, s16, s17
	s_add_u32 s16, s96, s16
	s_addc_u32 s17, s97, 0
	global_load_dwordx4 v[140:143], v122, s[6:7]
	global_load_dwordx4 v[150:153], v122, s[12:13]
	s_waitcnt vmcnt(0)
	ds_write_b32 v123, v140 offset:0
	ds_write_b32 v123, v141 offset:4
	ds_write_b32 v123, v142 offset:8
	ds_write_b32 v123, v143 offset:12
	ds_write_b32 v123, v150 offset:8320
	ds_write_b32 v123, v151 offset:8324
	ds_write_b32 v123, v152 offset:8328
	ds_write_b32 v123, v153 offset:8332
	s_waitcnt lgkmcnt(0)
	s_barrier
	s_mov_b64 s[26:27], s[16:17]
	s_add_i32 s4, s2, 128
	s_cmpk_lt_u32 s4, 0x200
	s_cselect_b32 s6, s28, s30
	s_cselect_b32 s7, s29, s31
	s_mov_b32 s16, 0x10500000
	s_cselect_b32 s16, 0x10100000, s16
	s_bfe_u32 s5, s4, 0x10008
	s_lshl_b32 s3, s5, 22
	s_add_u32 s6, s6, s3
	s_addc_u32 s7, s7, 0
	s_lshl_b32 s3, s5, 21
	s_add_i32 s16, s16, s3
	s_and_b32 s3, s4, 15
	s_bfe_u32 s5, s4, 0x40004
	s_lshl_b32 s17, s3, 18
	s_lshl_b32 s20, s5, 8
	s_add_i32 s17, s17, s20
	s_add_u32 s6, s6, s17
	s_addc_u32 s7, s7, 0
	s_add_u32 s12, s6, 0x20000
	s_addc_u32 s13, s7, 0
	s_lshl_b32 s17, s5, 17
	s_lshl_b32 s20, s3, 7
	s_add_i32 s17, s17, s20
	s_add_i32 s16, s16, s17
	s_add_u32 s16, s96, s16
	s_addc_u32 s17, s97, 0
	global_load_dwordx4 v[140:143], v122, s[6:7]
	global_load_dwordx4 v[150:153], v122, s[12:13]
	ds_read_b32 v154, v136 offset:0
	ds_read_b32 v155, v136 offset:260
	ds_read_b32 v156, v136 offset:520
	ds_read_b32 v157, v136 offset:780
	ds_read_b32 v158, v136 offset:1040
	ds_read_b32 v159, v136 offset:1300
	ds_read_b32 v160, v136 offset:1560
	ds_read_b32 v161, v136 offset:1820
	s_waitcnt lgkmcnt(0)
	v_cvt_pk_bf16_f32 v204, v154, v155
	v_cvt_pk_bf16_f32 v205, v156, v157
	v_cvt_pk_bf16_f32 v206, v158, v159
	v_cvt_pk_bf16_f32 v207, v160, v161
	global_store_dwordx4 v137, v[204:207], s[26:27]
	s_barrier
	s_waitcnt vmcnt(0)
	ds_write_b32 v123, v140 offset:0
	ds_write_b32 v123, v141 offset:4
	ds_write_b32 v123, v142 offset:8
	ds_write_b32 v123, v143 offset:12
	ds_write_b32 v123, v150 offset:8320
	ds_write_b32 v123, v151 offset:8324
	ds_write_b32 v123, v152 offset:8328
	ds_write_b32 v123, v153 offset:8332
	s_waitcnt lgkmcnt(0)
	s_barrier
	s_mov_b64 s[26:27], s[16:17]
	s_add_i32 s4, s2, 256
	s_cmpk_lt_u32 s4, 0x200
	s_cselect_b32 s6, s28, s30
	s_cselect_b32 s7, s29, s31
	s_mov_b32 s16, 0x10500000
	s_cselect_b32 s16, 0x10100000, s16
	s_bfe_u32 s5, s4, 0x10008
	s_lshl_b32 s3, s5, 22
	s_add_u32 s6, s6, s3
	s_addc_u32 s7, s7, 0
	s_lshl_b32 s3, s5, 21
	s_add_i32 s16, s16, s3
	s_and_b32 s3, s4, 15
	s_bfe_u32 s5, s4, 0x40004
	s_lshl_b32 s17, s3, 18
	s_lshl_b32 s20, s5, 8
	s_add_i32 s17, s17, s20
	s_add_u32 s6, s6, s17
	s_addc_u32 s7, s7, 0
	s_add_u32 s12, s6, 0x20000
	s_addc_u32 s13, s7, 0
	s_lshl_b32 s17, s5, 17
	s_lshl_b32 s20, s3, 7
	s_add_i32 s17, s17, s20
	s_add_i32 s16, s16, s17
	s_add_u32 s16, s96, s16
	s_addc_u32 s17, s97, 0
	global_load_dwordx4 v[140:143], v122, s[6:7]
	global_load_dwordx4 v[150:153], v122, s[12:13]
	ds_read_b32 v154, v136 offset:0
	ds_read_b32 v155, v136 offset:260
	ds_read_b32 v156, v136 offset:520
	ds_read_b32 v157, v136 offset:780
	ds_read_b32 v158, v136 offset:1040
	ds_read_b32 v159, v136 offset:1300
	ds_read_b32 v160, v136 offset:1560
	ds_read_b32 v161, v136 offset:1820
	s_waitcnt lgkmcnt(0)
	v_cvt_pk_bf16_f32 v204, v154, v155
	v_cvt_pk_bf16_f32 v205, v156, v157
	v_cvt_pk_bf16_f32 v206, v158, v159
	v_cvt_pk_bf16_f32 v207, v160, v161
	global_store_dwordx4 v137, v[204:207], s[26:27]
	s_barrier
	s_waitcnt vmcnt(0)
	ds_write_b32 v123, v140 offset:0
	ds_write_b32 v123, v141 offset:4
	ds_write_b32 v123, v142 offset:8
	ds_write_b32 v123, v143 offset:12
	ds_write_b32 v123, v150 offset:8320
	ds_write_b32 v123, v151 offset:8324
	ds_write_b32 v123, v152 offset:8328
	ds_write_b32 v123, v153 offset:8332
	s_waitcnt lgkmcnt(0)
	s_barrier
	s_mov_b64 s[26:27], s[16:17]
	s_add_i32 s4, s2, 384
	s_cmpk_lt_u32 s4, 0x200
	s_cselect_b32 s6, s28, s30
	s_cselect_b32 s7, s29, s31
	s_mov_b32 s16, 0x10500000
	s_cselect_b32 s16, 0x10100000, s16
	s_bfe_u32 s5, s4, 0x10008
	s_lshl_b32 s3, s5, 22
	s_add_u32 s6, s6, s3
	s_addc_u32 s7, s7, 0
	s_lshl_b32 s3, s5, 21
	s_add_i32 s16, s16, s3
	s_and_b32 s3, s4, 15
	s_bfe_u32 s5, s4, 0x40004
	s_lshl_b32 s17, s3, 18
	s_lshl_b32 s20, s5, 8
	s_add_i32 s17, s17, s20
	s_add_u32 s6, s6, s17
	s_addc_u32 s7, s7, 0
	s_add_u32 s12, s6, 0x20000
	s_addc_u32 s13, s7, 0
	s_lshl_b32 s17, s5, 17
	s_lshl_b32 s20, s3, 7
	s_add_i32 s17, s17, s20
	s_add_i32 s16, s16, s17
	s_add_u32 s16, s96, s16
	s_addc_u32 s17, s97, 0
	global_load_dwordx4 v[140:143], v122, s[6:7]
	global_load_dwordx4 v[150:153], v122, s[12:13]
	ds_read_b32 v154, v136 offset:0
	ds_read_b32 v155, v136 offset:260
	ds_read_b32 v156, v136 offset:520
	ds_read_b32 v157, v136 offset:780
	ds_read_b32 v158, v136 offset:1040
	ds_read_b32 v159, v136 offset:1300
	ds_read_b32 v160, v136 offset:1560
	ds_read_b32 v161, v136 offset:1820
	s_waitcnt lgkmcnt(0)
	v_cvt_pk_bf16_f32 v204, v154, v155
	v_cvt_pk_bf16_f32 v205, v156, v157
	v_cvt_pk_bf16_f32 v206, v158, v159
	v_cvt_pk_bf16_f32 v207, v160, v161
	global_store_dwordx4 v137, v[204:207], s[26:27]
	s_barrier
	s_waitcnt vmcnt(0)
	ds_write_b32 v123, v140 offset:0
	ds_write_b32 v123, v141 offset:4
	ds_write_b32 v123, v142 offset:8
	ds_write_b32 v123, v143 offset:12
	ds_write_b32 v123, v150 offset:8320
	ds_write_b32 v123, v151 offset:8324
	ds_write_b32 v123, v152 offset:8328
	ds_write_b32 v123, v153 offset:8332
	s_waitcnt lgkmcnt(0)
	s_barrier
	s_mov_b64 s[26:27], s[16:17]
	s_add_i32 s4, s2, 512
	s_cmpk_lt_u32 s4, 0x200
	s_cselect_b32 s6, s28, s30
	s_cselect_b32 s7, s29, s31
	s_mov_b32 s16, 0x10500000
	s_cselect_b32 s16, 0x10100000, s16
	s_bfe_u32 s5, s4, 0x10008
	s_lshl_b32 s3, s5, 22
	s_add_u32 s6, s6, s3
	s_addc_u32 s7, s7, 0
	s_lshl_b32 s3, s5, 21
	s_add_i32 s16, s16, s3
	s_and_b32 s3, s4, 15
	s_bfe_u32 s5, s4, 0x40004
	s_lshl_b32 s17, s3, 18
	s_lshl_b32 s20, s5, 8
	s_add_i32 s17, s17, s20
	s_add_u32 s6, s6, s17
	s_addc_u32 s7, s7, 0
	s_add_u32 s12, s6, 0x20000
	s_addc_u32 s13, s7, 0
	s_lshl_b32 s17, s5, 17
	s_lshl_b32 s20, s3, 7
	s_add_i32 s17, s17, s20
	s_add_i32 s16, s16, s17
	s_add_u32 s16, s96, s16
	s_addc_u32 s17, s97, 0
	global_load_dwordx4 v[140:143], v122, s[6:7]
	global_load_dwordx4 v[150:153], v122, s[12:13]
	ds_read_b32 v154, v136 offset:0
	ds_read_b32 v155, v136 offset:260
	ds_read_b32 v156, v136 offset:520
	ds_read_b32 v157, v136 offset:780
	ds_read_b32 v158, v136 offset:1040
	ds_read_b32 v159, v136 offset:1300
	ds_read_b32 v160, v136 offset:1560
	ds_read_b32 v161, v136 offset:1820
	s_waitcnt lgkmcnt(0)
	v_cvt_pk_bf16_f32 v204, v154, v155
	v_cvt_pk_bf16_f32 v205, v156, v157
	v_cvt_pk_bf16_f32 v206, v158, v159
	v_cvt_pk_bf16_f32 v207, v160, v161
	global_store_dwordx4 v137, v[204:207], s[26:27]
	s_barrier
	s_waitcnt vmcnt(0)
	ds_write_b32 v123, v140 offset:0
	ds_write_b32 v123, v141 offset:4
	ds_write_b32 v123, v142 offset:8
	ds_write_b32 v123, v143 offset:12
	ds_write_b32 v123, v150 offset:8320
	ds_write_b32 v123, v151 offset:8324
	ds_write_b32 v123, v152 offset:8328
	ds_write_b32 v123, v153 offset:8332
	s_waitcnt lgkmcnt(0)
	s_barrier
	s_mov_b64 s[26:27], s[16:17]
	s_add_i32 s4, s2, 640
	s_cmpk_lt_u32 s4, 0x200
	s_cselect_b32 s6, s28, s30
	s_cselect_b32 s7, s29, s31
	s_mov_b32 s16, 0x10500000
	s_cselect_b32 s16, 0x10100000, s16
	s_bfe_u32 s5, s4, 0x10008
	s_lshl_b32 s3, s5, 22
	s_add_u32 s6, s6, s3
	s_addc_u32 s7, s7, 0
	s_lshl_b32 s3, s5, 21
	s_add_i32 s16, s16, s3
	s_and_b32 s3, s4, 15
	s_bfe_u32 s5, s4, 0x40004
	s_lshl_b32 s17, s3, 18
	s_lshl_b32 s20, s5, 8
	s_add_i32 s17, s17, s20
	s_add_u32 s6, s6, s17
	s_addc_u32 s7, s7, 0
	s_add_u32 s12, s6, 0x20000
	s_addc_u32 s13, s7, 0
	s_lshl_b32 s17, s5, 17
	s_lshl_b32 s20, s3, 7
	s_add_i32 s17, s17, s20
	s_add_i32 s16, s16, s17
	s_add_u32 s16, s96, s16
	s_addc_u32 s17, s97, 0
	global_load_dwordx4 v[140:143], v122, s[6:7]
	global_load_dwordx4 v[150:153], v122, s[12:13]
	ds_read_b32 v154, v136 offset:0
	ds_read_b32 v155, v136 offset:260
	ds_read_b32 v156, v136 offset:520
	ds_read_b32 v157, v136 offset:780
	ds_read_b32 v158, v136 offset:1040
	ds_read_b32 v159, v136 offset:1300
	ds_read_b32 v160, v136 offset:1560
	ds_read_b32 v161, v136 offset:1820
	s_waitcnt lgkmcnt(0)
	v_cvt_pk_bf16_f32 v204, v154, v155
	v_cvt_pk_bf16_f32 v205, v156, v157
	v_cvt_pk_bf16_f32 v206, v158, v159
	v_cvt_pk_bf16_f32 v207, v160, v161
	global_store_dwordx4 v137, v[204:207], s[26:27]
	s_barrier
	s_waitcnt vmcnt(0)
	ds_write_b32 v123, v140 offset:0
	ds_write_b32 v123, v141 offset:4
	ds_write_b32 v123, v142 offset:8
	ds_write_b32 v123, v143 offset:12
	ds_write_b32 v123, v150 offset:8320
	ds_write_b32 v123, v151 offset:8324
	ds_write_b32 v123, v152 offset:8328
	ds_write_b32 v123, v153 offset:8332
	s_waitcnt lgkmcnt(0)
	s_barrier
	s_mov_b64 s[26:27], s[16:17]
	s_add_i32 s4, s2, 768
	s_cmpk_lt_u32 s4, 0x200
	s_cselect_b32 s6, s28, s30
	s_cselect_b32 s7, s29, s31
	s_mov_b32 s16, 0x10500000
	s_cselect_b32 s16, 0x10100000, s16
	s_bfe_u32 s5, s4, 0x10008
	s_lshl_b32 s3, s5, 22
	s_add_u32 s6, s6, s3
	s_addc_u32 s7, s7, 0
	s_lshl_b32 s3, s5, 21
	s_add_i32 s16, s16, s3
	s_and_b32 s3, s4, 15
	s_bfe_u32 s5, s4, 0x40004
	s_lshl_b32 s17, s3, 18
	s_lshl_b32 s20, s5, 8
	s_add_i32 s17, s17, s20
	s_add_u32 s6, s6, s17
	s_addc_u32 s7, s7, 0
	s_add_u32 s12, s6, 0x20000
	s_addc_u32 s13, s7, 0
	s_lshl_b32 s17, s5, 17
	s_lshl_b32 s20, s3, 7
	s_add_i32 s17, s17, s20
	s_add_i32 s16, s16, s17
	s_add_u32 s16, s96, s16
	s_addc_u32 s17, s97, 0
	global_load_dwordx4 v[140:143], v122, s[6:7]
	global_load_dwordx4 v[150:153], v122, s[12:13]
	ds_read_b32 v154, v136 offset:0
	ds_read_b32 v155, v136 offset:260
	ds_read_b32 v156, v136 offset:520
	ds_read_b32 v157, v136 offset:780
	ds_read_b32 v158, v136 offset:1040
	ds_read_b32 v159, v136 offset:1300
	ds_read_b32 v160, v136 offset:1560
	ds_read_b32 v161, v136 offset:1820
	s_waitcnt lgkmcnt(0)
	v_cvt_pk_bf16_f32 v204, v154, v155
	v_cvt_pk_bf16_f32 v205, v156, v157
	v_cvt_pk_bf16_f32 v206, v158, v159
	v_cvt_pk_bf16_f32 v207, v160, v161
	global_store_dwordx4 v137, v[204:207], s[26:27]
	s_barrier
	s_waitcnt vmcnt(0)
	ds_write_b32 v123, v140 offset:0
	ds_write_b32 v123, v141 offset:4
	ds_write_b32 v123, v142 offset:8
	ds_write_b32 v123, v143 offset:12
	ds_write_b32 v123, v150 offset:8320
	ds_write_b32 v123, v151 offset:8324
	ds_write_b32 v123, v152 offset:8328
	ds_write_b32 v123, v153 offset:8332
	s_waitcnt lgkmcnt(0)
	s_barrier
	s_mov_b64 s[26:27], s[16:17]
	s_add_i32 s4, s2, 896
	s_cmpk_lt_u32 s4, 0x200
	s_cselect_b32 s6, s28, s30
	s_cselect_b32 s7, s29, s31
	s_mov_b32 s16, 0x10500000
	s_cselect_b32 s16, 0x10100000, s16
	s_bfe_u32 s5, s4, 0x10008
	s_lshl_b32 s3, s5, 22
	s_add_u32 s6, s6, s3
	s_addc_u32 s7, s7, 0
	s_lshl_b32 s3, s5, 21
	s_add_i32 s16, s16, s3
	s_and_b32 s3, s4, 15
	s_bfe_u32 s5, s4, 0x40004
	s_lshl_b32 s17, s3, 18
	s_lshl_b32 s20, s5, 8
	s_add_i32 s17, s17, s20
	s_add_u32 s6, s6, s17
	s_addc_u32 s7, s7, 0
	s_add_u32 s12, s6, 0x20000
	s_addc_u32 s13, s7, 0
	s_lshl_b32 s17, s5, 17
	s_lshl_b32 s20, s3, 7
	s_add_i32 s17, s17, s20
	s_add_i32 s16, s16, s17
	s_add_u32 s16, s96, s16
	s_addc_u32 s17, s97, 0
	global_load_dwordx4 v[140:143], v122, s[6:7]
	global_load_dwordx4 v[150:153], v122, s[12:13]
	ds_read_b32 v154, v136 offset:0
	ds_read_b32 v155, v136 offset:260
	ds_read_b32 v156, v136 offset:520
	ds_read_b32 v157, v136 offset:780
	ds_read_b32 v158, v136 offset:1040
	ds_read_b32 v159, v136 offset:1300
	ds_read_b32 v160, v136 offset:1560
	ds_read_b32 v161, v136 offset:1820
	s_waitcnt lgkmcnt(0)
	v_cvt_pk_bf16_f32 v204, v154, v155
	v_cvt_pk_bf16_f32 v205, v156, v157
	v_cvt_pk_bf16_f32 v206, v158, v159
	v_cvt_pk_bf16_f32 v207, v160, v161
	global_store_dwordx4 v137, v[204:207], s[26:27]
	s_barrier
	s_waitcnt vmcnt(0)
	ds_write_b32 v123, v140 offset:0
	ds_write_b32 v123, v141 offset:4
	ds_write_b32 v123, v142 offset:8
	ds_write_b32 v123, v143 offset:12
	ds_write_b32 v123, v150 offset:8320
	ds_write_b32 v123, v151 offset:8324
	ds_write_b32 v123, v152 offset:8328
	ds_write_b32 v123, v153 offset:8332
	s_waitcnt lgkmcnt(0)
	s_barrier
	s_mov_b64 s[26:27], s[16:17]
	ds_read_b32 v154, v136 offset:0
	ds_read_b32 v155, v136 offset:260
	ds_read_b32 v156, v136 offset:520
	ds_read_b32 v157, v136 offset:780
	ds_read_b32 v158, v136 offset:1040
	ds_read_b32 v159, v136 offset:1300
	ds_read_b32 v160, v136 offset:1560
	ds_read_b32 v161, v136 offset:1820
	s_waitcnt lgkmcnt(0)
	v_cvt_pk_bf16_f32 v204, v154, v155
	v_cvt_pk_bf16_f32 v205, v156, v157
	v_cvt_pk_bf16_f32 v206, v158, v159
	v_cvt_pk_bf16_f32 v207, v160, v161
	global_store_dwordx4 v137, v[204:207], s[26:27]
	s_barrier
	s_branch .LBB0_243
